# all stacked: plus gain-load hoist, p copy unroll, w_down epilogue prefetch, b64 clearing
# speedup vs baseline: 1.0058x; 1.0058x over previous
; __device__ __forceinline__ unsigned pk2(float lo, float hi) { unsigned r; asm("v_cvt_pk_bf16_f32 %0, %1, %2" : "=v"(r) : "v"(lo), "v"(hi)); return r; }
; #define GIN(i) GPTR(const float, args.in[i])
; __global__ void __launch_bounds__(NWAVES * 64, 2) hymba_fwd(Args args) {
;     ...
;             { int tid = threadIdx.x; asm volatile("" : "+v"(tid));
;               const int e0 = bx * (NWAVES * 64) + tid, NE = G * NWAVES * 64;
;               const float* __restrict__ pp = GIN(I_PP) + (size_t)L * MP * PLE; bf16* __restrict__ pbo = PB;
; #pragma unroll 4
;               for (int e = e0; e < MP * (PLE / 8); e += NE) { const f32x4 a = *(const f32x4*)(pp + (size_t)e * 8), c = *(const f32x4*)(pp + (size_t)e * 8 + 4);
;                   v4u o; o.x = pk2(a[0], a[1]); o.y = pk2(a[2], a[3]); o.z = pk2(c[0], c[1]); o.w = pk2(c[2], c[3]); *(v4u*)(pbo + (size_t)e * 8) = o; }
.LBB0_676:
	s_cmp_lg_u32 s92, 0x20000
	s_cbranch_scc1 .Lpconv_loop
	global_load_dwordx4 v[10:13], v[6:7], off offset:-16
	global_load_dwordx4 v[14:17], v[6:7], off
	v_lshl_add_u64 v[6:7], v[6:7], 0, s[90:91]
	global_load_dwordx4 v[108:111], v[6:7], off offset:-16
	global_load_dwordx4 v[112:115], v[6:7], off
	v_lshl_add_u64 v[6:7], v[6:7], 0, s[90:91]
	global_load_dwordx4 v[116:119], v[6:7], off offset:-16
	global_load_dwordx4 v[120:123], v[6:7], off
	v_lshl_add_u64 v[6:7], v[6:7], 0, s[90:91]
	global_load_dwordx4 v[124:127], v[6:7], off offset:-16
	global_load_dwordx4 v[128:131], v[6:7], off
	s_waitcnt vmcnt(6)
	v_cvt_pk_bf16_f32 v10, v10, v11
	v_cvt_pk_bf16_f32 v11, v12, v13
	v_cvt_pk_bf16_f32 v12, v14, v15
	v_cvt_pk_bf16_f32 v13, v16, v17
	global_store_dwordx4 v[8:9], v[10:13], off
	v_lshl_add_u64 v[8:9], v[8:9], 0, s[28:29]
	s_waitcnt vmcnt(5)
	v_cvt_pk_bf16_f32 v108, v108, v109
	v_cvt_pk_bf16_f32 v109, v110, v111
	v_cvt_pk_bf16_f32 v110, v112, v113
	v_cvt_pk_bf16_f32 v111, v114, v115
	global_store_dwordx4 v[8:9], v[108:111], off
	v_lshl_add_u64 v[8:9], v[8:9], 0, s[28:29]
	s_waitcnt vmcnt(4)
	v_cvt_pk_bf16_f32 v116, v116, v117
	v_cvt_pk_bf16_f32 v117, v118, v119
	v_cvt_pk_bf16_f32 v118, v120, v121
	v_cvt_pk_bf16_f32 v119, v122, v123
	global_store_dwordx4 v[8:9], v[116:119], off
	v_lshl_add_u64 v[8:9], v[8:9], 0, s[28:29]
	s_waitcnt vmcnt(3)
	v_cvt_pk_bf16_f32 v124, v124, v125
	v_cvt_pk_bf16_f32 v125, v126, v127
	v_cvt_pk_bf16_f32 v126, v128, v129
	v_cvt_pk_bf16_f32 v127, v130, v131
	global_store_dwordx4 v[8:9], v[124:127], off
	s_branch .LBB0_677
